# barrier: write-through (sc1) stores, no L2 writeback; follower L1 invalidate issued before polling instead of after release; XCD leader waits for its invalidate before releasing
# baseline (speedup 1.0000x reference)
.LBB0_695:
	s_or_b64 exec, exec, s[20:21]
	v_cvt_f32_u32_e32 v5, v3
	s_waitcnt vmcnt(0)
	v_readfirstlane_b32 s20, v4
	v_sub_u32_e32 v4, 0, v3
	v_rcp_iflag_f32_e32 v5, v5
	v_add_u32_e32 v6, s20, v0
	v_mul_f32_e32 v5, 0x4f7ffffe, v5
	v_cvt_u32_f32_e32 v5, v5
	v_mul_lo_u32 v0, v4, v5
	v_mul_hi_u32 v0, v5, v0
	v_add_u32_e32 v0, v5, v0
	v_mul_hi_u32 v0, v6, v0
	v_mul_lo_u32 v4, v0, v3
	v_sub_u32_e32 v4, v6, v4
	v_add_u32_e32 v5, 1, v0
	v_cmp_ge_u32_e32 vcc, v4, v3
	s_nop 1
	v_cndmask_b32_e32 v0, v0, v5, vcc
	v_sub_u32_e32 v5, v4, v3
	v_cndmask_b32_e32 v4, v4, v5, vcc
	v_add_u32_e32 v5, 1, v0
	v_cmp_ge_u32_e32 vcc, v4, v3
	v_add_u32_e32 v4, 1, v6
	s_nop 0
	v_cndmask_b32_e32 v0, v0, v5, vcc
	v_mul_lo_u32 v5, v3, v0
	v_add_u32_e32 v3, v5, v3
	v_cmp_ne_u32_e32 vcc, v4, v3
	s_and_saveexec_b64 s[20:21], vcc
	s_xor_b64 s[20:21], exec, s[20:21]
	s_cbranch_execz .LBB0_710
	v_readlane_b32 s4, v252, 32
	v_readlane_b32 s5, v252, 33
	s_waitcnt lgkmcnt(0)
	s_nop 3
	buffer_inv sc1
	global_load_dword v2, v1, s[4:5] sc1
	s_waitcnt vmcnt(0)
	v_cmp_eq_u32_e32 vcc, v2, v0
	s_and_saveexec_b64 s[40:41], vcc
	s_cbranch_execz .LBB0_709
	s_mov_b32 s24, 1
	s_mov_b64 s[42:43], 0
	s_branch .LBB0_699

.LBB0_709:
	s_or_b64 exec, exec, s[40:41]
	s_waitcnt vmcnt(0)
	s_waitcnt vmcnt(0)
